# job2 prologue de-serialisation: first K tile f32 cache loads and fq load issued before the Q fragment wait (counted wait)
# speedup vs baseline: 1.0049x; 1.0049x over previous
.LBB0_979:
	s_ashr_i32 s8, s54, 3
	s_ashr_i32 s9, s8, 31
	s_lshl_b64 s[6:7], s[8:9], 6
	s_add_u32 s10, s6, 0x4000
	s_addc_u32 s11, s7, 0
	s_lshl_b64 s[6:7], s[10:11], 10
	s_add_u32 s6, s78, s6
	s_addc_u32 s7, s79, s7
	s_lshl_b32 s12, s54, 6
	s_and_b32 s30, s12, 0x1c0
	v_readlane_b32 s56, v245, 0
	s_lshl_b32 s55, s30, 1
	v_readlane_b32 s57, v245, 1
	s_add_u32 s6, s6, s55
	v_readlane_b32 s58, v245, 2
	v_readlane_b32 s59, v245, 3
	v_readlane_b32 s60, v245, 4
	v_readlane_b32 s61, v245, 5
	v_readlane_b32 s62, v245, 6
	v_readlane_b32 s63, v245, 7
	s_mov_b64 s[44:45], s[56:57]
	s_addc_u32 s7, s7, 0
	s_lshl_b64 s[36:37], s[8:9], 21
	s_lshl_b64 s[12:13], s[8:9], 23
	s_mov_b64 s[48:49], s[60:61]
	s_add_u32 s12, s48, s12
	s_addc_u32 s13, s49, s13
	s_lshl_b32 s43, s30, 2
	s_add_u32 s12, s12, s43
	s_addc_u32 s13, s13, 0
	s_mul_i32 s30, s54, 0x4100
	v_mov_b32_e32 v4, v0
	s_mul_hi_i32 s31, s54, 0x4100
	s_add_u32 s30, s84, s30
	s_addc_u32 s31, s85, s31
	v_readfirstlane_b32 s38, v4
	s_ashr_i32 s38, s38, 6
	s_lshr_b32 s39, s38, 31
	s_add_i32 s40, s38, s39
	s_ashr_i32 s39, s40, 1
	s_and_b32 s40, s40, -2
	s_sub_i32 s42, s38, s40
	s_mov_b64 s[46:47], s[58:59]
	s_mov_b64 s[50:51], s[62:63]
	v_and_b32_e32 v133, 31, v4
	s_lshl_b32 s56, s42, 5
	v_or_b32_e32 v130, s56, v133
	v_ashrrev_i32_e32 v131, 31, v130
	v_bfe_u32 v1, v4, 5, 1
	v_lshlrev_b64 v[2:3], 10, v[130:131]
	v_lshl_add_u64 v[2:3], s[6:7], 0, v[2:3]
	v_lshlrev_b32_e32 v26, 4, v1
	v_mov_b32_e32 v27, v199
	v_lshl_add_u64 v[2:3], v[2:3], 0, v[26:27]
	global_load_dwordx4 v[6:9], v[2:3], off
	global_load_dwordx4 v[10:13], v[2:3], off offset:32
	global_load_dwordx4 v[14:17], v[2:3], off offset:64
	global_load_dwordx4 v[18:21], v[2:3], off offset:96
	s_lshl_b32 s6, s42, 12
	v_and_b32_e32 v139, 63, v4
	s_add_i32 s6, s6, 0
	s_add_i32 s6, s6, 0x12400
	v_lshlrev_b32_e32 v2, 4, v139
	v_add_u32_e32 v172, s6, v2
	v_lshl_add_u64 v[2:3], v[130:131], 2, s[30:31]
	v_add_co_u32_e32 v2, vcc, s0, v2
	v_cmp_gt_i32_e64 s[6:7], s91, v4
	s_nop 0
	v_addc_co_u32_e32 v3, vcc, 0, v3, vcc
	v_mov_b32_e32 v173, 0
	v_mov_b32_e32 v174, 0
	v_readlane_b32 s64, v245, 8
	v_readlane_b32 s65, v245, 9
	v_readlane_b32 s66, v245, 10
	v_readlane_b32 s67, v245, 11
	v_readlane_b32 s68, v245, 12
	v_readlane_b32 s69, v245, 13
	v_readlane_b32 s70, v245, 14
	v_readlane_b32 s71, v245, 15
	v_ashrrev_i32_e32 v240, 3, v4
	v_ashrrev_i32_e32 v241, 31, v240
	global_load_dword v2, v[2:3], off
	v_and_b32_e32 v248, 7, v4
	v_lshlrev_b64 v[242:243], 11, v[240:241]
	v_lshl_add_u64 v[242:243], s[12:13], 0, v[242:243]
	v_lshlrev_b32_e32 v250, 4, v248
	v_mov_b32_e32 v251, v199
	v_lshl_add_u64 v[242:243], v[242:243], 0, v[250:251]
	v_add_co_u32_e32 v246, vcc, 0x20000, v242
	global_load_dwordx4 v[74:77], v[242:243], off nt
	global_load_dwordx4 v[78:81], v[242:243], off offset:128 nt
	v_addc_co_u32_e32 v247, vcc, 0, v243, vcc
	global_load_dwordx4 v[66:69], v[246:247], off nt
	global_load_dwordx4 v[70:73], v[246:247], off offset:128 nt
	v_add_co_u32_e32 v246, vcc, 0x40000, v242
	s_nop 1
	v_addc_co_u32_e32 v247, vcc, 0, v243, vcc
	v_add_co_u32_e32 v242, vcc, 0x60000, v242
	global_load_dwordx4 v[82:85], v[246:247], off nt
	global_load_dwordx4 v[86:89], v[246:247], off offset:128 nt
	v_addc_co_u32_e32 v243, vcc, 0, v243, vcc
	global_load_dwordx4 v[90:93], v[242:243], off nt
	global_load_dwordx4 v[94:97], v[242:243], off offset:128 nt
	s_waitcnt vmcnt(9)
	ds_write_b128 v172, v[6:9]
	ds_write_b128 v172, v[10:13] offset:1024
	ds_write_b128 v172, v[14:17] offset:2048
	ds_write_b128 v172, v[18:21] offset:3072
	v_ashrrev_i32_e32 v6, 3, v4
	v_ashrrev_i32_e32 v7, 31, v6
	v_and_b32_e32 v3, 7, v4
	v_lshlrev_b32_e32 v198, 4, v3
	s_and_saveexec_b64 s[40:41], s[6:7]
	s_cbranch_execz .LBB0_981
	v_ashrrev_i32_e32 v5, 31, v4
	v_lshl_add_u64 v[8:9], v[4:5], 2, s[30:31]
	global_load_dword v174, v[8:9], off
